# residual GEMM: first four residual quads of the tile loaded before the K loop into dead VGPRs, epilogue copies them instead of waiting; first-iteration stage wait skipped when stage 0 is already compl
# baseline (speedup 1.0000x reference)
.LBB0_841:
	v_bfe_u32 v19, v18, 4, 2
	v_and_b32_e32 v20, 15, v18
	v_lshlrev_b32_e32 v22, 4, v19
	v_lshlrev_b32_e32 v18, 2, v18
	s_and_b32 s27, s23, 3
	s_lshr_b32 s28, s20, 6
	s_waitcnt vmcnt(0)
	v_lshl_or_b32 v144, s21, 6, v20
	v_lshl_or_b32 v20, v20, 6, v22
	s_lshl_b32 s20, s21, 13
	v_and_b32_e32 v18, 32, v18
	v_bitop3_b32 v22, v20, s20, v18 bitop3:0xde
	s_lshl_b32 s20, s27, 12
	v_bitop3_b32 v145, v20, s20, v18 bitop3:0xde
	v_readlane_b32 s20, v249, 56
	v_readlane_b32 s21, v249, 57
	s_add_u32 s20, s20, 0x100000
	s_addc_u32 s21, s21, 0
	s_add_i32 m0, s14, 0x18000
	v_lshl_add_u64 v[0:1], v[0:1], 0, s[88:89]
	s_waitcnt vmcnt(2)
	s_barrier
	v_readlane_b32 s52, v250, 8
	v_readlane_b32 s53, v250, 9
	v_lshlrev_b32_e32 v232, 3, v19
	v_lshl_or_b32 v232, s27, 5, v232
	v_lshl_add_u32 v234, s52, 8, v144
	v_lshl_or_b32 v232, s53, 8, v232
	v_ashrrev_i32_e32 v235, 31, v234
	v_ashrrev_i32_e32 v233, 31, v232
	v_lshlrev_b64 v[234:235], 11, v[234:235]
	v_lshl_add_u64 v[234:235], s[80:81], 0, v[234:235]
	v_lshl_add_u64 v[254:255], v[232:233], 1, v[234:235]
	global_load_dwordx4 v[232:235], v[254:255], off
	global_load_dwordx4 v[236:239], v[254:255], off offset:256
	s_mov_b64 s[52:53], 0x8000
	v_lshl_add_u64 v[254:255], s[52:53], 0, v[254:255]
	global_load_dwordx4 v[240:243], v[254:255], off
	global_load_dwordx4 v[244:247], v[254:255], off offset:256
	global_load_lds_dwordx4 v[0:1], off
	v_lshl_add_u64 v[0:1], v[2:3], 0, s[88:89]
	s_add_i32 m0, s14, 0x1a000
	s_add_i32 s29, s14, 0x8000
	global_load_lds_dwordx4 v[0:1], off
	v_lshl_add_u64 v[0:1], v[8:9], 0, s[88:89]
	s_mov_b32 m0, s29
	s_add_i32 s33, s14, 0xa000
	global_load_lds_dwordx4 v[0:1], off
	v_lshl_add_u64 v[0:1], v[10:11], 0, s[88:89]
	s_mov_b32 m0, s33
	s_add_i32 s48, s28, -2
	global_load_lds_dwordx4 v[0:1], off
	s_add_i32 m0, s14, 0x1c000
	v_lshl_add_u64 v[0:1], v[4:5], 0, s[88:89]
	global_load_lds_dwordx4 v[0:1], off
	v_lshl_add_u64 v[0:1], v[6:7], 0, s[88:89]
	s_add_i32 m0, s14, 0x1e000
	v_lshlrev_b32_e32 v21, 3, v19
	global_load_lds_dwordx4 v[0:1], off
	v_add_u32_e32 v0, v17, v15
	v_add_lshl_u32 v0, v0, v16, 1
	v_mov_b32_e32 v1, v197
	v_lshl_add_u64 v[134:135], s[12:13], 0, v[0:1]
	v_add_u32_e32 v0, v14, v12
	s_cmpk_lt_u32 s22, 0x100
	v_add_lshl_u32 v0, v0, v13, 1
	v_lshl_or_b32 v146, s27, 5, v21
	s_cselect_b64 s[22:23], -1, 0
	s_mov_b32 s49, 0
	v_cmp_eq_u32_e64 s[40:41], 0, v19
	v_lshl_add_u64 v[136:137], s[12:13], 0, v[0:1]
	v_add_u32_e32 v147, 0, v22
	v_readlane_b32 s36, v250, 9
	v_readlane_b32 s51, v250, 8
	s_branch .LBB0_844

.LBB0_854:
	s_add_u32 s34, s34, 0x80
	s_addc_u32 s35, s35, 0
	s_add_u32 s46, s46, 0x100
	v_mov_b32_e32 v228, 0
	v_mov_b32_e32 v229, 0
	v_mov_b32_e32 v230, 0
	v_mov_b32_e32 v231, 0
	s_addc_u32 s47, s47, 0
	s_mov_b32 s44, 0
	s_waitcnt lgkmcnt(0)
	v_mfma_f32_32x32x16_bf16 v[0:15], v[228:231], v[228:231], 0
	v_mfma_f32_32x32x16_bf16 v[16:31], v[228:231], v[228:231], 0
	v_mfma_f32_32x32x16_bf16 v[32:47], v[228:231], v[228:231], 0
	v_mfma_f32_32x32x16_bf16 v[48:63], v[228:231], v[228:231], 0
	v_mfma_f32_32x32x16_bf16 v[64:79], v[228:231], v[228:231], 0
	v_mfma_f32_32x32x16_bf16 v[80:95], v[228:231], v[228:231], 0
	v_mfma_f32_32x32x16_bf16 v[96:111], v[228:231], v[228:231], 0
	v_mfma_f32_32x32x16_bf16 v[112:127], v[228:231], v[228:231], 0
	s_cmp_lg_u32 s49, 1
	s_cbranch_scc1 .Lfw_2
	s_waitcnt vmcnt(10)
	s_barrier
.Lfw_2:
.LBB0_855:
	s_add_i32 s52, s44, 2
	s_add_u32 s53, s34, 0x80
	s_addc_u32 s45, s35, 0
	s_add_i32 s56, 0, 0x10000
	s_cmp_eq_u32 s48, s44
	s_cselect_b32 s45, s25, s45
	s_cselect_b32 s44, s24, s53
	v_add_u32_e32 v142, s56, v145
	s_cselect_b32 s55, s31, s47
	s_cselect_b32 s54, s30, s46
	s_add_i32 s53, 0, 0x14000
	ds_read_b128 v[138:141], v142
	ds_read_b128 v[148:151], v142 offset:1024
	ds_read_b128 v[152:155], v142 offset:2048
	ds_read_b128 v[156:159], v142 offset:3072
	v_add_u32_e32 v142, s53, v145
	ds_read_b128 v[160:163], v142
	ds_read_b128 v[164:167], v142 offset:1024
	ds_read_b128 v[168:171], v142 offset:2048
	ds_read_b128 v[172:175], v142 offset:3072
	v_lshl_add_u64 v[142:143], s[34:35], 0, v[134:135]
	s_add_i32 m0, s14, 0xc000
	ds_read_b128 v[176:179], v147
	ds_read_b128 v[180:183], v147 offset:1024
	ds_read_b128 v[184:187], v147 offset:2048
	ds_read_b128 v[188:191], v147 offset:3072
	ds_read_b128 v[192:195], v147 offset:4096
	ds_read_b128 v[204:207], v147 offset:5120
	ds_read_b128 v[208:211], v147 offset:6144
	ds_read_b128 v[212:215], v147 offset:7168
	global_load_lds_dwordx4 v[142:143], off
	v_lshl_add_u64 v[142:143], s[34:35], 0, v[136:137]
	s_add_i32 m0, s14, 0xe000
	s_nop 0
	global_load_lds_dwordx4 v[142:143], off
	s_cmp_lg_u32 s52, 2
	s_cbranch_scc1 .Lree_w0
	s_cmp_eq_u32 s49, 1
	s_cbranch_scc1 .Lree_w1
.Lree_w0:
	s_waitcnt vmcnt(8)
.Lree_w1:
	s_waitcnt lgkmcnt(0)
	s_barrier
	s_setprio 1
	s_waitcnt lgkmcnt(0)
	v_mfma_f32_16x16x32_bf16 v[124:127], v[138:141], v[176:179], v[124:127]
	v_mfma_f32_16x16x32_bf16 v[120:123], v[152:155], v[176:179], v[120:123]
	v_mfma_f32_16x16x32_bf16 v[108:111], v[138:141], v[184:187], v[108:111]
	v_mfma_f32_16x16x32_bf16 v[104:107], v[152:155], v[184:187], v[104:107]
	v_mfma_f32_16x16x32_bf16 v[92:95], v[138:141], v[192:195], v[92:95]
	v_mfma_f32_16x16x32_bf16 v[88:91], v[152:155], v[192:195], v[88:91]
	v_mfma_f32_16x16x32_bf16 v[76:79], v[138:141], v[208:211], v[76:79]
	v_mfma_f32_16x16x32_bf16 v[72:75], v[152:155], v[208:211], v[72:75]
	v_mfma_f32_16x16x32_bf16 v[124:127], v[148:151], v[180:183], v[124:127]
	v_mfma_f32_16x16x32_bf16 v[120:123], v[156:159], v[180:183], v[120:123]
	v_mfma_f32_16x16x32_bf16 v[108:111], v[148:151], v[188:191], v[108:111]
	v_mfma_f32_16x16x32_bf16 v[104:107], v[156:159], v[188:191], v[104:107]
	v_mfma_f32_16x16x32_bf16 v[92:95], v[148:151], v[204:207], v[92:95]
	v_mfma_f32_16x16x32_bf16 v[88:91], v[156:159], v[204:207], v[88:91]
	v_mfma_f32_16x16x32_bf16 v[76:79], v[148:151], v[212:215], v[76:79]
	v_mfma_f32_16x16x32_bf16 v[72:75], v[156:159], v[212:215], v[72:75]
	s_setprio 0
	s_setprio 1
	v_mfma_f32_16x16x32_bf16 v[116:119], v[160:163], v[176:179], v[116:119]
	v_mfma_f32_16x16x32_bf16 v[112:115], v[168:171], v[176:179], v[112:115]
	v_mfma_f32_16x16x32_bf16 v[100:103], v[160:163], v[184:187], v[100:103]
	v_mfma_f32_16x16x32_bf16 v[96:99], v[168:171], v[184:187], v[96:99]
	v_mfma_f32_16x16x32_bf16 v[84:87], v[160:163], v[192:195], v[84:87]
	v_mfma_f32_16x16x32_bf16 v[80:83], v[168:171], v[192:195], v[80:83]
	v_mfma_f32_16x16x32_bf16 v[68:71], v[160:163], v[208:211], v[68:71]
	v_mfma_f32_16x16x32_bf16 v[64:67], v[168:171], v[208:211], v[64:67]
	v_mfma_f32_16x16x32_bf16 v[116:119], v[164:167], v[180:183], v[116:119]
	v_mfma_f32_16x16x32_bf16 v[112:115], v[172:175], v[180:183], v[112:115]
	v_mfma_f32_16x16x32_bf16 v[100:103], v[164:167], v[188:191], v[100:103]
	v_mfma_f32_16x16x32_bf16 v[96:99], v[172:175], v[188:191], v[96:99]
	v_mfma_f32_16x16x32_bf16 v[84:87], v[164:167], v[204:207], v[84:87]
	v_mfma_f32_16x16x32_bf16 v[80:83], v[172:175], v[204:207], v[80:83]
	v_mfma_f32_16x16x32_bf16 v[68:71], v[164:167], v[212:215], v[68:71]
	v_mfma_f32_16x16x32_bf16 v[64:67], v[172:175], v[212:215], v[64:67]
	s_setprio 0
	s_barrier
	s_add_i32 s56, s56, s11
	v_lshl_add_u64 v[142:143], s[54:55], 0, v[196:197]
	s_mov_b32 m0, s56
	ds_read_b128 v[176:179], v147 offset:16384
	ds_read_b128 v[180:183], v147 offset:17408
	ds_read_b128 v[184:187], v147 offset:18432
	ds_read_b128 v[188:191], v147 offset:19456
	ds_read_b128 v[192:195], v147 offset:20480
	ds_read_b128 v[204:207], v147 offset:21504
	ds_read_b128 v[208:211], v147 offset:22528
	ds_read_b128 v[212:215], v147 offset:23552
	global_load_lds_dwordx4 v[142:143], off
	s_add_i32 m0, s56, 0x2000
	v_lshl_add_u64 v[216:217], s[54:55], 0, v[128:129]
	s_add_u32 s54, s54, s12
	s_addc_u32 s55, s55, 0
	s_add_i32 s53, s53, s11
	global_load_lds_dwordx4 v[216:217], off
	v_lshl_add_u64 v[218:219], s[54:55], 0, v[196:197]
	s_mov_b32 m0, s53
	v_lshl_add_u64 v[220:221], s[54:55], 0, v[128:129]
	global_load_lds_dwordx4 v[218:219], off
	s_add_i32 m0, s53, 0x2000
	v_lshl_add_u64 v[226:227], s[44:45], 0, v[132:133]
	global_load_lds_dwordx4 v[220:221], off
	s_mov_b32 m0, s14
	v_lshl_add_u64 v[228:229], s[44:45], 0, v[130:131]
	global_load_lds_dwordx4 v[226:227], off
	s_mov_b32 m0, s15
	s_nop 0
	global_load_lds_dwordx4 v[228:229], off
	s_waitcnt vmcnt(8)
	s_waitcnt lgkmcnt(0)
	s_barrier
	s_setprio 1
	s_waitcnt lgkmcnt(0)
	v_mfma_f32_16x16x32_bf16 v[60:63], v[138:141], v[176:179], v[60:63]
	v_mfma_f32_16x16x32_bf16 v[56:59], v[152:155], v[176:179], v[56:59]
	v_mfma_f32_16x16x32_bf16 v[44:47], v[138:141], v[184:187], v[44:47]
	v_mfma_f32_16x16x32_bf16 v[40:43], v[152:155], v[184:187], v[40:43]
	v_mfma_f32_16x16x32_bf16 v[28:31], v[138:141], v[192:195], v[28:31]
	v_mfma_f32_16x16x32_bf16 v[24:27], v[152:155], v[192:195], v[24:27]
	v_mfma_f32_16x16x32_bf16 v[12:15], v[138:141], v[208:211], v[12:15]
	v_mfma_f32_16x16x32_bf16 v[8:11], v[152:155], v[208:211], v[8:11]
	v_mfma_f32_16x16x32_bf16 v[60:63], v[148:151], v[180:183], v[60:63]
	v_mfma_f32_16x16x32_bf16 v[56:59], v[156:159], v[180:183], v[56:59]
	v_mfma_f32_16x16x32_bf16 v[44:47], v[148:151], v[188:191], v[44:47]
	v_mfma_f32_16x16x32_bf16 v[40:43], v[156:159], v[188:191], v[40:43]
	v_mfma_f32_16x16x32_bf16 v[28:31], v[148:151], v[204:207], v[28:31]
	v_mfma_f32_16x16x32_bf16 v[24:27], v[156:159], v[204:207], v[24:27]
	v_mfma_f32_16x16x32_bf16 v[12:15], v[148:151], v[212:215], v[12:15]
	v_mfma_f32_16x16x32_bf16 v[8:11], v[156:159], v[212:215], v[8:11]
	s_setprio 0
	s_setprio 1
	v_mfma_f32_16x16x32_bf16 v[52:55], v[160:163], v[176:179], v[52:55]
	v_mfma_f32_16x16x32_bf16 v[48:51], v[168:171], v[176:179], v[48:51]
	v_mfma_f32_16x16x32_bf16 v[36:39], v[160:163], v[184:187], v[36:39]
	v_mfma_f32_16x16x32_bf16 v[32:35], v[168:171], v[184:187], v[32:35]
	v_mfma_f32_16x16x32_bf16 v[20:23], v[160:163], v[192:195], v[20:23]
	v_mfma_f32_16x16x32_bf16 v[16:19], v[168:171], v[192:195], v[16:19]
	v_mfma_f32_16x16x32_bf16 v[4:7], v[160:163], v[208:211], v[4:7]
	v_mfma_f32_16x16x32_bf16 v[0:3], v[168:171], v[208:211], v[0:3]
	v_mfma_f32_16x16x32_bf16 v[52:55], v[164:167], v[180:183], v[52:55]
	v_mfma_f32_16x16x32_bf16 v[48:51], v[172:175], v[180:183], v[48:51]
	v_mfma_f32_16x16x32_bf16 v[36:39], v[164:167], v[188:191], v[36:39]
	v_mfma_f32_16x16x32_bf16 v[32:35], v[172:175], v[188:191], v[32:35]
	v_mfma_f32_16x16x32_bf16 v[20:23], v[164:167], v[204:207], v[20:23]
	v_mfma_f32_16x16x32_bf16 v[16:19], v[172:175], v[204:207], v[16:19]
	v_mfma_f32_16x16x32_bf16 v[4:7], v[164:167], v[212:215], v[4:7]
	v_mfma_f32_16x16x32_bf16 v[0:3], v[172:175], v[212:215], v[0:3]
	s_setprio 0
	s_barrier
	s_add_i32 s53, 0, 0x18000
	s_add_i32 s54, 0, 0x1c000
	v_add_u32_e32 v156, s53, v145
	v_add_u32_e32 v172, s54, v145
	ds_read_b128 v[138:141], v156
	ds_read_b128 v[148:151], v156 offset:1024
	ds_read_b128 v[152:155], v156 offset:2048
	ds_read_b128 v[156:159], v156 offset:3072
	ds_read_b128 v[160:163], v172
	ds_read_b128 v[164:167], v172 offset:1024
	ds_read_b128 v[168:171], v172 offset:2048
	ds_read_b128 v[172:175], v172 offset:3072
	s_add_u32 s44, s44, s12
	s_addc_u32 s45, s45, 0
	s_mov_b32 m0, s17
	v_lshl_add_u64 v[230:231], s[44:45], 0, v[132:133]
	ds_read_b128 v[176:179], v147 offset:32768
	ds_read_b128 v[180:183], v147 offset:33792
	ds_read_b128 v[184:187], v147 offset:34816
	ds_read_b128 v[188:191], v147 offset:35840
	ds_read_b128 v[192:195], v147 offset:36864
	ds_read_b128 v[204:207], v147 offset:37888
	ds_read_b128 v[208:211], v147 offset:38912
	ds_read_b128 v[212:215], v147 offset:39936
	global_load_lds_dwordx4 v[230:231], off
	v_lshl_add_u64 v[230:231], s[44:45], 0, v[130:131]
	s_mov_b32 m0, s26
	s_nop 0
	global_load_lds_dwordx4 v[230:231], off
	s_waitcnt vmcnt(8)
	s_waitcnt lgkmcnt(0)
	s_barrier
	s_setprio 1
	s_waitcnt lgkmcnt(0)
	v_mfma_f32_16x16x32_bf16 v[124:127], v[138:141], v[176:179], v[124:127]
	v_mfma_f32_16x16x32_bf16 v[120:123], v[152:155], v[176:179], v[120:123]
	v_mfma_f32_16x16x32_bf16 v[108:111], v[138:141], v[184:187], v[108:111]
	v_mfma_f32_16x16x32_bf16 v[104:107], v[152:155], v[184:187], v[104:107]
	v_mfma_f32_16x16x32_bf16 v[92:95], v[138:141], v[192:195], v[92:95]
	v_mfma_f32_16x16x32_bf16 v[88:91], v[152:155], v[192:195], v[88:91]
	v_mfma_f32_16x16x32_bf16 v[76:79], v[138:141], v[208:211], v[76:79]
	v_mfma_f32_16x16x32_bf16 v[72:75], v[152:155], v[208:211], v[72:75]
	v_mfma_f32_16x16x32_bf16 v[124:127], v[148:151], v[180:183], v[124:127]
	v_mfma_f32_16x16x32_bf16 v[120:123], v[156:159], v[180:183], v[120:123]
	v_mfma_f32_16x16x32_bf16 v[108:111], v[148:151], v[188:191], v[108:111]
	v_mfma_f32_16x16x32_bf16 v[104:107], v[156:159], v[188:191], v[104:107]
	v_mfma_f32_16x16x32_bf16 v[92:95], v[148:151], v[204:207], v[92:95]
	v_mfma_f32_16x16x32_bf16 v[88:91], v[156:159], v[204:207], v[88:91]
	v_mfma_f32_16x16x32_bf16 v[76:79], v[148:151], v[212:215], v[76:79]
	v_mfma_f32_16x16x32_bf16 v[72:75], v[156:159], v[212:215], v[72:75]
	s_setprio 0
	s_setprio 1
	v_mfma_f32_16x16x32_bf16 v[116:119], v[160:163], v[176:179], v[116:119]
	v_mfma_f32_16x16x32_bf16 v[112:115], v[168:171], v[176:179], v[112:115]
	v_mfma_f32_16x16x32_bf16 v[100:103], v[160:163], v[184:187], v[100:103]
	v_mfma_f32_16x16x32_bf16 v[96:99], v[168:171], v[184:187], v[96:99]
	v_mfma_f32_16x16x32_bf16 v[84:87], v[160:163], v[192:195], v[84:87]
	v_mfma_f32_16x16x32_bf16 v[80:83], v[168:171], v[192:195], v[80:83]
	v_mfma_f32_16x16x32_bf16 v[68:71], v[160:163], v[208:211], v[68:71]
	v_mfma_f32_16x16x32_bf16 v[64:67], v[168:171], v[208:211], v[64:67]
	v_mfma_f32_16x16x32_bf16 v[116:119], v[164:167], v[180:183], v[116:119]
	v_mfma_f32_16x16x32_bf16 v[112:115], v[172:175], v[180:183], v[112:115]
	v_mfma_f32_16x16x32_bf16 v[100:103], v[164:167], v[188:191], v[100:103]
	v_mfma_f32_16x16x32_bf16 v[96:99], v[172:175], v[188:191], v[96:99]
	v_mfma_f32_16x16x32_bf16 v[84:87], v[164:167], v[204:207], v[84:87]
	v_mfma_f32_16x16x32_bf16 v[80:83], v[172:175], v[204:207], v[80:83]
	v_mfma_f32_16x16x32_bf16 v[68:71], v[164:167], v[212:215], v[68:71]
	v_mfma_f32_16x16x32_bf16 v[64:67], v[172:175], v[212:215], v[64:67]
	s_setprio 0
	s_barrier
	s_add_i32 s44, s53, s11
	v_lshl_add_u64 v[142:143], v[142:143], 0, s[88:89]
	s_mov_b32 m0, s44
	ds_read_b128 v[176:179], v147 offset:49152
	ds_read_b128 v[180:183], v147 offset:50176
	ds_read_b128 v[184:187], v147 offset:51200
	ds_read_b128 v[188:191], v147 offset:52224
	ds_read_b128 v[192:195], v147 offset:53248
	ds_read_b128 v[204:207], v147 offset:54272
	ds_read_b128 v[208:211], v147 offset:55296
	ds_read_b128 v[212:215], v147 offset:56320
	global_load_lds_dwordx4 v[142:143], off
	v_lshl_add_u64 v[142:143], v[216:217], 0, s[88:89]
	s_add_i32 m0, s44, 0x2000
	s_add_i32 s44, s54, s11
	global_load_lds_dwordx4 v[142:143], off
	v_lshl_add_u64 v[142:143], v[218:219], 0, s[88:89]
	s_mov_b32 m0, s44
	s_nop 0
	global_load_lds_dwordx4 v[142:143], off
	v_lshl_add_u64 v[142:143], v[220:221], 0, s[88:89]
	s_add_i32 m0, s44, 0x2000
	s_nop 0
	global_load_lds_dwordx4 v[142:143], off
	v_lshl_add_u64 v[142:143], v[226:227], 0, s[88:89]
	s_mov_b32 m0, s29
	s_nop 0
	global_load_lds_dwordx4 v[142:143], off
	v_lshl_add_u64 v[142:143], v[228:229], 0, s[88:89]
	s_mov_b32 m0, s33
	s_nop 0
	global_load_lds_dwordx4 v[142:143], off
	s_waitcnt vmcnt(8)
	s_waitcnt lgkmcnt(0)
	s_barrier
	s_setprio 1
	s_waitcnt lgkmcnt(0)
	v_mfma_f32_16x16x32_bf16 v[60:63], v[138:141], v[176:179], v[60:63]
	v_mfma_f32_16x16x32_bf16 v[56:59], v[152:155], v[176:179], v[56:59]
	v_mfma_f32_16x16x32_bf16 v[44:47], v[138:141], v[184:187], v[44:47]
	v_mfma_f32_16x16x32_bf16 v[40:43], v[152:155], v[184:187], v[40:43]
	v_mfma_f32_16x16x32_bf16 v[28:31], v[138:141], v[192:195], v[28:31]
	v_mfma_f32_16x16x32_bf16 v[24:27], v[152:155], v[192:195], v[24:27]
	v_mfma_f32_16x16x32_bf16 v[12:15], v[138:141], v[208:211], v[12:15]
	v_mfma_f32_16x16x32_bf16 v[8:11], v[152:155], v[208:211], v[8:11]
	v_mfma_f32_16x16x32_bf16 v[60:63], v[148:151], v[180:183], v[60:63]
	v_mfma_f32_16x16x32_bf16 v[56:59], v[156:159], v[180:183], v[56:59]
	v_mfma_f32_16x16x32_bf16 v[44:47], v[148:151], v[188:191], v[44:47]
	v_mfma_f32_16x16x32_bf16 v[40:43], v[156:159], v[188:191], v[40:43]
	v_mfma_f32_16x16x32_bf16 v[28:31], v[148:151], v[204:207], v[28:31]
	v_mfma_f32_16x16x32_bf16 v[24:27], v[156:159], v[204:207], v[24:27]
	v_mfma_f32_16x16x32_bf16 v[12:15], v[148:151], v[212:215], v[12:15]
	v_mfma_f32_16x16x32_bf16 v[8:11], v[156:159], v[212:215], v[8:11]
	s_setprio 0
	s_setprio 1
	v_mfma_f32_16x16x32_bf16 v[52:55], v[160:163], v[176:179], v[52:55]
	v_mfma_f32_16x16x32_bf16 v[48:51], v[168:171], v[176:179], v[48:51]
	v_mfma_f32_16x16x32_bf16 v[36:39], v[160:163], v[184:187], v[36:39]
	v_mfma_f32_16x16x32_bf16 v[32:35], v[168:171], v[184:187], v[32:35]
	v_mfma_f32_16x16x32_bf16 v[20:23], v[160:163], v[192:195], v[20:23]
	v_mfma_f32_16x16x32_bf16 v[16:19], v[168:171], v[192:195], v[16:19]
	v_mfma_f32_16x16x32_bf16 v[4:7], v[160:163], v[208:211], v[4:7]
	v_mfma_f32_16x16x32_bf16 v[0:3], v[168:171], v[208:211], v[0:3]
	v_mfma_f32_16x16x32_bf16 v[52:55], v[164:167], v[180:183], v[52:55]
	v_mfma_f32_16x16x32_bf16 v[48:51], v[172:175], v[180:183], v[48:51]
	v_mfma_f32_16x16x32_bf16 v[36:39], v[164:167], v[188:191], v[36:39]
	v_mfma_f32_16x16x32_bf16 v[32:35], v[172:175], v[188:191], v[32:35]
	v_mfma_f32_16x16x32_bf16 v[20:23], v[164:167], v[204:207], v[20:23]
	v_mfma_f32_16x16x32_bf16 v[16:19], v[172:175], v[204:207], v[16:19]
	v_mfma_f32_16x16x32_bf16 v[4:7], v[164:167], v[212:215], v[4:7]
	v_mfma_f32_16x16x32_bf16 v[0:3], v[172:175], v[212:215], v[0:3]
	s_setprio 0
	s_barrier
	s_add_u32 s34, s34, 0x100
	s_addc_u32 s35, s35, 0
	s_add_u32 s46, s46, 0x100
	s_addc_u32 s47, s47, 0
	s_cmp_ge_u32 s52, s28
	s_mov_b32 s44, s52
	s_cbranch_scc0 .LBB0_855
	s_and_b64 vcc, exec, s[22:23]
	s_cbranch_vccz .LBB0_858
	s_barrier
.LBB0_858:
	v_lshl_add_u32 v140, s51, 8, v144
	v_ashrrev_i32_e32 v141, 31, v140
	v_lshl_or_b32 v138, s36, 8, v146
	v_lshlrev_b64 v[142:143], 11, v[140:141]
	v_ashrrev_i32_e32 v139, 31, v138
	v_lshl_add_u64 v[142:143], s[80:81], 0, v[142:143]
	v_lshl_add_u64 v[142:143], v[138:139], 1, v[142:143]
	s_cmp_lg_u32 s49, 1
	s_cbranch_scc1 .Lree_full
	v_mov_b64_e32 v[148:149], v[232:233]
	v_mov_b64_e32 v[150:151], v[234:235]
	v_mov_b64_e32 v[156:157], v[236:237]
	v_mov_b64_e32 v[158:159], v[238:239]
	v_mov_b64_e32 v[160:161], v[240:241]
	v_mov_b64_e32 v[162:163], v[242:243]
	v_mov_b64_e32 v[164:165], v[244:245]
	v_mov_b64_e32 v[166:167], v[246:247]
	s_branch .Lree_join
.Lree_full:
	global_load_dwordx4 v[148:151], v[142:143], off
	global_load_dwordx4 v[156:159], v[142:143], off offset:256
	s_mov_b64 s[52:53], 0x8000
	v_lshl_add_u64 v[226:227], s[52:53], 0, v[142:143]
	global_load_dwordx4 v[160:163], v[226:227], off
	global_load_dwordx4 v[164:167], v[226:227], off offset:256
.Lree_join:
	s_mov_b64 s[52:53], 0x10000
	v_lshl_add_u64 v[226:227], s[52:53], 0, v[142:143]
	global_load_dwordx4 v[168:171], v[226:227], off
	global_load_dwordx4 v[172:175], v[226:227], off offset:256
	s_mov_b64 s[52:53], 0x18000
	v_lshl_add_u64 v[226:227], s[52:53], 0, v[142:143]
	global_load_dwordx4 v[176:179], v[226:227], off
	global_load_dwordx4 v[180:183], v[226:227], off offset:256
	s_mov_b64 s[52:53], 0x40000
	v_lshl_add_u64 v[226:227], s[52:53], 0, v[142:143]
	global_load_dwordx4 v[184:187], v[226:227], off
	global_load_dwordx4 v[188:191], v[226:227], off offset:256
	s_mov_b64 s[52:53], 0x48000
	v_lshl_add_u64 v[226:227], s[52:53], 0, v[142:143]
	global_load_dwordx4 v[192:195], v[226:227], off
	global_load_dwordx4 v[204:207], v[226:227], off offset:256
	s_mov_b64 s[52:53], 0x50000
	v_lshl_add_u64 v[226:227], s[52:53], 0, v[142:143]
	global_load_dwordx4 v[208:211], v[226:227], off
	global_load_dwordx4 v[212:215], v[226:227], off offset:256
	s_mov_b64 s[52:53], 0x58000
	v_lshl_add_u64 v[226:227], s[52:53], 0, v[142:143]
	global_load_dwordx4 v[216:219], v[226:227], off
	global_load_dwordx4 v[228:231], v[226:227], off offset:256
	s_lshl_b32 s34, s36, 2
	s_ashr_i32 s35, s34, 31
	s_waitcnt vmcnt(15)
	v_lshlrev_b32_e32 v152, 16, v148
	v_fmac_f32_e32 v152, s2, v124
	v_and_b32_e32 v124, 0xffff0000, v148
	v_fmac_f32_e32 v124, s2, v125
	v_cvt_pk_bf16_f32 v124, v152, v124
	s_nop 0
	v_and_b32_e32 v148, 0xffff0000, v124
	v_lshlrev_b32_e32 v125, 16, v124
	v_mul_f32_e32 v148, v148, v148
	v_fmac_f32_e32 v148, v125, v125
	v_lshlrev_b32_e32 v125, 16, v149
	v_fmac_f32_e32 v125, s2, v126
	v_and_b32_e32 v126, 0xffff0000, v149
	v_fmac_f32_e32 v126, s2, v127
	v_cvt_pk_bf16_f32 v125, v125, v126
	s_nop 0
	v_and_b32_e32 v127, 0xffff0000, v125
	v_lshlrev_b32_e32 v126, 16, v125
	v_mul_f32_e32 v127, v127, v127
	v_fmac_f32_e32 v127, v126, v126
	v_lshlrev_b32_e32 v126, 16, v150
	v_fmac_f32_e32 v126, s2, v120
	v_and_b32_e32 v120, 0xffff0000, v150
	v_fmac_f32_e32 v120, s2, v121
	v_cvt_pk_bf16_f32 v126, v126, v120
	v_add_f32_e32 v127, v148, v127
	v_and_b32_e32 v121, 0xffff0000, v126
	v_lshlrev_b32_e32 v120, 16, v126
	v_mul_f32_e32 v121, v121, v121
	v_fmac_f32_e32 v121, v120, v120
	v_add_f32_e32 v120, v127, v121
	v_lshlrev_b32_e32 v121, 16, v151
	v_fmac_f32_e32 v121, s2, v122
	v_and_b32_e32 v122, 0xffff0000, v151
	v_fmac_f32_e32 v122, s2, v123
	v_cvt_pk_bf16_f32 v127, v121, v122
	global_store_dwordx4 v[142:143], v[124:127], off
	v_and_b32_e32 v122, 0xffff0000, v127
	v_lshlrev_b32_e32 v121, 16, v127
	v_mul_f32_e32 v122, v122, v122
	v_fmac_f32_e32 v122, v121, v121
	v_add_f32_e32 v148, v120, v122
	s_waitcnt vmcnt(15)
	v_mov_b64_e32 v[120:121], v[156:157]
	v_mov_b64_e32 v[122:123], v[158:159]
	v_lshlrev_b32_e32 v124, 16, v120
	v_fmac_f32_e32 v124, s2, v116
	v_and_b32_e32 v116, 0xffff0000, v120
	v_fmac_f32_e32 v116, s2, v117
	v_cvt_pk_bf16_f32 v116, v124, v116
	s_nop 0
	v_and_b32_e32 v120, 0xffff0000, v116
	v_lshlrev_b32_e32 v117, 16, v116
	v_mul_f32_e32 v120, v120, v120
	v_fmac_f32_e32 v120, v117, v117
	v_lshlrev_b32_e32 v117, 16, v121
	v_fmac_f32_e32 v117, s2, v118
	v_and_b32_e32 v118, 0xffff0000, v121
	v_fmac_f32_e32 v118, s2, v119
	v_cvt_pk_bf16_f32 v117, v117, v118
	v_add_f32_e32 v120, v148, v120
	v_and_b32_e32 v119, 0xffff0000, v117
	v_lshlrev_b32_e32 v118, 16, v117
	v_mul_f32_e32 v119, v119, v119
	v_fmac_f32_e32 v119, v118, v118
	v_lshlrev_b32_e32 v118, 16, v122
	v_fmac_f32_e32 v118, s2, v112
	v_and_b32_e32 v112, 0xffff0000, v122
	v_fmac_f32_e32 v112, s2, v113
	v_cvt_pk_bf16_f32 v118, v118, v112
	v_add_f32_e32 v119, v120, v119
	v_and_b32_e32 v113, 0xffff0000, v118
	v_lshlrev_b32_e32 v112, 16, v118
	v_mul_f32_e32 v113, v113, v113
	v_fmac_f32_e32 v113, v112, v112
	v_add_f32_e32 v112, v119, v113
	v_lshlrev_b32_e32 v113, 16, v123
	v_fmac_f32_e32 v113, s2, v114
	v_and_b32_e32 v114, 0xffff0000, v123
	v_fmac_f32_e32 v114, s2, v115
	v_cvt_pk_bf16_f32 v119, v113, v114
	global_store_dwordx4 v[142:143], v[116:119], off offset:256
	v_and_b32_e32 v114, 0xffff0000, v119
	v_lshlrev_b32_e32 v113, 16, v119
	v_mul_f32_e32 v114, v114, v114
	v_fmac_f32_e32 v114, v113, v113
	v_add_f32_e32 v112, v112, v114
	v_and_b32_e32 v114, 64, v222
	v_xor_b32_e32 v113, 16, v222
	v_add_u32_e32 v115, 64, v114
	v_cmp_lt_i32_e32 vcc, v113, v115
	s_nop 1
	v_cndmask_b32_e32 v113, v222, v113, vcc
	v_lshlrev_b32_e32 v114, 2, v113
	v_mov_b32_e32 v113, v112
	s_nop 1
	v_permlane16_swap_b32_e32 v112, v113
	s_waitcnt lgkmcnt(0)
	v_add_f32_e32 v112, v112, v113
	v_xor_b32_e32 v113, 32, v222
	v_cmp_lt_i32_e32 vcc, v113, v115
	s_nop 1
	v_cndmask_b32_e32 v113, v222, v113, vcc
	v_lshlrev_b32_e32 v115, 2, v113
	v_mov_b32_e32 v113, v112
	s_nop 1
	v_permlane32_swap_b32_e32 v112, v113
	s_and_saveexec_b64 s[44:45], s[40:41]
	s_cbranch_execz .LBB0_860
	v_lshlrev_b64 v[116:117], 6, v[140:141]
	v_lshl_add_u64 v[116:117], s[20:21], 0, v[116:117]
	v_lshl_add_u64 v[116:117], s[34:35], 2, v[116:117]
	s_lshl_b32 s36, s27, 2
	v_lshl_add_u64 v[116:117], v[116:117], 0, s[36:37]
	s_waitcnt lgkmcnt(0)
	v_add_f32_e32 v112, v112, v113
	global_store_dword v[116:117], v112, off
